# phase_h row loops: hoisted the 21 row-invariant gain/scale/shift vector loads into the preheader (both inlined copies)
# baseline (speedup 1.0000x reference)
; DEVI int lbid() { int t = __builtin_amdgcn_workgroup_id_x(); asm volatile("" : "+s"(t)); return t; }
; DEVI int ltid() { int t = __builtin_amdgcn_workitem_id_x(); asm volatile("" : "+v"(t)); return t; }
; __device__ void phase_h(const float* __restrict__ x, const float* __restrict__ g, const float* __restrict__ sh, const float* __restrict__ sc, bf16_t* __restrict__ H) {
;   const int wave = ltid() >> 6, lane = ltid() & 63;
;   for (int row = lbid() * 8 + wave; row < T; row += gridDim.x * 8) {
;     const float* xr = x + (size_t)row * D;
;     f32x4 v[8]; float ss = 0.f;
; #pragma unroll
;     for (int i = 0; i < 8; ++i) { v[i] = __builtin_nontemporal_load((const f32x4*)(xr + i * 256 + lane * 4));   ss += v[i][0] * v[i][0] + v[i][1] * v[i][1] + v[i][2] * v[i][2] + v[i][3] * v[i][3]; }
;     ss = wave_sum(ss);
;     const float rstd = rsqrtf(ss * (1.f / D) + 1e-6f);
; #pragma unroll
;     for (int i = 0; i < 8; ++i) {
;       const int c = i * 256 + lane * 4;
;       f32x4 gg = *(const f32x4*)(g + c), s1 = *(const f32x4*)(sc + c), s0 = *(const f32x4*)(sh + c);
.LBB0_32:
	s_and_b64 vcc, exec, s[8:9]
	s_cbranch_vccz .LBB0_38
	v_readlane_b32 s0, v250, 0
	s_cmp_eq_u32 s0, 10
	s_mov_b64 s[10:11], -1
	s_cbranch_scc0 .LBB0_38
	v_mov_b32_e32 v0, v169
	v_readlane_b32 s0, v252, 0
	s_waitcnt vmcnt(0)
	v_ashrrev_i32_e32 v2, 6, v0
	v_mov_b32_e32 v0, v169
	s_nop 0
	v_lshl_add_u32 v38, s0, 3, v2
	v_cmp_gt_i32_e32 vcc, s74, v38
	s_and_saveexec_b64 s[10:11], vcc
	v_readlane_b32 s4, v252, 8
	s_mov_b32 s5, 0x800000
	s_cbranch_execz .LBB0_37
	s_load_dwordx2 s[0:1], s[84:85], 0x30
	v_readlane_b32 s2, v251, 28
	v_readlane_b32 s3, v251, 29
	s_add_u32 s8, s2, 0x8000
	s_addc_u32 s9, s3, 0
	v_lshlrev_b32_e32 v0, 2, v0
	s_add_u32 s12, s2, 0x6000
	v_and_b32_e32 v26, 0xfc, v0
	v_lshlrev_b32_e32 v0, 2, v26
	s_addc_u32 s13, s3, 0
	s_lshl_b64 s[2:3], s[54:55], 2
	global_load_dwordx4 v[10:13], v0, s[8:9]
	s_waitcnt lgkmcnt(0)
	s_add_u32 s40, s0, s2
	s_addc_u32 s41, s1, s3
	global_load_dwordx4 v[2:5], v0, s[12:13]
	global_load_dwordx4 v[6:9], v0, s[40:41]
	v_and_b32_e32 v14, 64, v185
	v_xor_b32_e32 v16, 32, v185
	v_add_u32_e32 v14, 64, v14
	v_xor_b32_e32 v18, 16, v185
	v_cmp_lt_i32_e32 vcc, v16, v14
	v_xor_b32_e32 v20, 8, v185
	v_xor_b32_e32 v22, 4, v185
	v_cndmask_b32_e32 v16, v185, v16, vcc
	v_cmp_lt_i32_e32 vcc, v18, v14
	v_xor_b32_e32 v24, 2, v185
	v_xor_b32_e32 v27, 1, v185
	v_cndmask_b32_e32 v18, v185, v18, vcc
	v_cmp_lt_i32_e32 vcc, v20, v14
	v_readlane_b32 s0, v251, 34
	v_readlane_b32 s1, v251, 35
	v_cndmask_b32_e32 v20, v185, v20, vcc
	v_cmp_lt_i32_e32 vcc, v22, v14
	v_lshl_add_u64 v[40:41], s[0:1], 0, v[0:1]
	v_lshlrev_b32_e32 v88, 2, v16
	v_cndmask_b32_e32 v22, v185, v22, vcc
	v_cmp_lt_i32_e32 vcc, v24, v14
	v_lshlrev_b32_e32 v89, 2, v18
	v_lshlrev_b32_e32 v90, 2, v20
	v_cndmask_b32_e32 v24, v185, v24, vcc
	v_cmp_lt_i32_e32 vcc, v27, v14
	v_lshlrev_b32_e32 v91, 2, v22
	v_lshlrev_b32_e32 v92, 2, v24
	v_cndmask_b32_e32 v14, v185, v27, vcc
	v_lshlrev_b32_e32 v93, 2, v14
	v_or_b32_e32 v14, 0x400, v0
	v_or_b32_e32 v16, 0x800, v0
	v_or_b32_e32 v18, 0xc00, v0
	v_or_b32_e32 v20, 0x1000, v0
	v_or_b32_e32 v22, 0x1400, v0
	v_or_b32_e32 v24, 0x1800, v0
	v_lshl_add_u64 v[66:67], s[40:41], 0, v[0:1]
	v_or_b32_e32 v0, 0x1c00, v0
	v_readlane_b32 s0, v251, 32
	v_mov_b32_e32 v15, v1
	v_mov_b32_e32 v17, v1
	v_mov_b32_e32 v19, v1
	v_mov_b32_e32 v21, v1
	v_mov_b32_e32 v23, v1
	v_mov_b32_e32 v25, v1
	v_lshl_add_u64 v[74:75], s[40:41], 0, v[0:1]
	v_lshl_add_u64 v[76:77], s[8:9], 0, v[0:1]
	v_lshl_add_u64 v[82:83], s[12:13], 0, v[0:1]
	v_lshlrev_b32_e32 v0, 1, v26
	v_readlane_b32 s1, v251, 33
	v_lshl_add_u64 v[42:43], s[8:9], 0, v[14:15]
	v_lshl_add_u64 v[44:45], s[12:13], 0, v[14:15]
	v_lshl_add_u64 v[46:47], s[8:9], 0, v[16:17]
	v_lshl_add_u64 v[48:49], s[12:13], 0, v[16:17]
	v_lshl_add_u64 v[50:51], s[8:9], 0, v[18:19]
	v_lshl_add_u64 v[52:53], s[12:13], 0, v[18:19]
	v_lshl_add_u64 v[54:55], s[8:9], 0, v[20:21]
	v_lshl_add_u64 v[56:57], s[12:13], 0, v[20:21]
	v_lshl_add_u64 v[58:59], s[8:9], 0, v[22:23]
	v_lshl_add_u64 v[60:61], s[12:13], 0, v[22:23]
	v_lshl_add_u64 v[62:63], s[8:9], 0, v[24:25]
	v_lshl_add_u64 v[64:65], s[12:13], 0, v[24:25]
	v_lshl_add_u64 v[68:69], s[40:41], 0, v[20:21]
	v_lshl_add_u64 v[70:71], s[40:41], 0, v[22:23]
	v_lshl_add_u64 v[72:73], s[40:41], 0, v[24:25]
	v_lshl_add_u64 v[84:85], s[0:1], 0, v[0:1]
	s_mov_b64 s[12:13], 0
	s_waitcnt vmcnt(2)
	v_pk_add_f32 v[78:79], v[12:13], 1.0 op_sel_hi:[1,0]
	v_pk_add_f32 v[80:81], v[10:11], 1.0 op_sel_hi:[1,0]
	global_load_dwordx4 v[112:115], v[66:67], off offset:1024
	global_load_dwordx4 v[116:119], v[42:43], off
	global_load_dwordx4 v[120:123], v[44:45], off
	global_load_dwordx4 v[124:127], v[66:67], off offset:2048
	global_load_dwordx4 v[128:131], v[46:47], off
	global_load_dwordx4 v[132:135], v[48:49], off
	global_load_dwordx4 v[136:139], v[66:67], off offset:3072
	global_load_dwordx4 v[140:143], v[50:51], off
	global_load_dwordx4 v[144:147], v[52:53], off
	global_load_dwordx4 v[148:151], v[68:69], off
	global_load_dwordx4 v[152:155], v[54:55], off
	global_load_dwordx4 v[156:159], v[56:57], off
	global_load_dwordx4 v[160:163], v[70:71], off
	global_load_dwordx4 v[164:167], v[58:59], off
	global_load_dwordx4 v[194:197], v[60:61], off
	global_load_dwordx4 v[198:201], v[72:73], off
	global_load_dwordx4 v[202:205], v[62:63], off
	global_load_dwordx4 v[206:209], v[64:65], off
	global_load_dwordx4 v[210:213], v[74:75], off
	global_load_dwordx4 v[214:217], v[76:77], off
	global_load_dwordx4 v[218:221], v[82:83], off
	s_waitcnt vmcnt(0)
; __device__ void phase_h(const float* __restrict__ x, const float* __restrict__ g, const float* __restrict__ sh, const float* __restrict__ sc, bf16_t* __restrict__ H) {
;     ...
;     const float* xr = x + (size_t)row * D;
;     f32x4 v[8]; float ss = 0.f;
; #pragma unroll
;     for (int i = 0; i < 8; ++i) { v[i] = __builtin_nontemporal_load((const f32x4*)(xr + i * 256 + lane * 4));   ss += v[i][0] * v[i][0] + v[i][1] * v[i][1] + v[i][2] * v[i][2] + v[i][3] * v[i][3]; }
;     ss = wave_sum(ss);
.LBB0_36:
	v_ashrrev_i32_e32 v39, 31, v38
	v_lshlrev_b64 v[10:11], 13, v[38:39]
	v_lshl_add_u64 v[10:11], v[40:41], 0, v[10:11]
	global_load_dwordx4 v[94:97], v[10:11], off nt
	global_load_dwordx4 v[34:37], v[10:11], off offset:1024 nt
	global_load_dwordx4 v[30:33], v[10:11], off offset:2048 nt
	global_load_dwordx4 v[26:29], v[10:11], off offset:3072 nt
	v_add_co_u32_e32 v10, vcc, s57, v10
	s_waitcnt vmcnt(3)
	v_mul_f32_e32 v0, v95, v95
	v_addc_co_u32_e32 v11, vcc, 0, v11, vcc
	global_load_dwordx4 v[22:25], v[10:11], off nt
	global_load_dwordx4 v[14:17], v[10:11], off offset:1024 nt
	s_waitcnt vmcnt(4)
	v_mul_f32_e32 v12, v35, v35
	v_fmac_f32_e32 v0, v94, v94
	v_fmac_f32_e32 v12, v34, v34
	v_fmac_f32_e32 v0, v96, v96
	v_fmac_f32_e32 v12, v36, v36
	v_fmac_f32_e32 v0, v97, v97
	v_fmac_f32_e32 v12, v37, v37
	v_add_f32_e32 v0, v0, v12
	s_waitcnt vmcnt(3)
	v_mul_f32_e32 v12, v31, v31
	v_fmac_f32_e32 v12, v30, v30
	v_fmac_f32_e32 v12, v32, v32
	v_fmac_f32_e32 v12, v33, v33
	v_add_f32_e32 v0, v0, v12
	s_waitcnt vmcnt(2)
	v_mul_f32_e32 v12, v27, v27
	v_fmac_f32_e32 v12, v26, v26
	v_fmac_f32_e32 v12, v28, v28
	v_fmac_f32_e32 v12, v29, v29
	v_add_f32_e32 v0, v0, v12
	s_waitcnt vmcnt(1)
	v_mov_b32_e32 v18, v23
	s_waitcnt vmcnt(0)
	v_mov_b32_e32 v19, v15
	v_mov_b32_e32 v12, v22
	v_mov_b32_e32 v13, v14
	v_pk_mul_f32 v[18:19], v[18:19], v[18:19]
	s_nop 0
	v_pk_fma_f32 v[12:13], v[12:13], v[12:13], v[18:19]
	v_mov_b32_e32 v18, v24
	v_mov_b32_e32 v19, v16
	v_pk_fma_f32 v[12:13], v[18:19], v[18:19], v[12:13]
	v_mov_b32_e32 v18, v25
	v_mov_b32_e32 v19, v17
	v_pk_fma_f32 v[12:13], v[18:19], v[18:19], v[12:13]
	s_nop 0
	v_add_f32_e32 v0, v0, v12
	v_add_f32_e32 v0, v0, v13
	global_load_dwordx4 v[18:21], v[10:11], off offset:2048 nt
	s_nop 0
	global_load_dwordx4 v[10:13], v[10:11], off offset:3072 nt
	s_waitcnt vmcnt(1)
	v_mov_b32_e32 v98, v19
	s_waitcnt vmcnt(0)
	v_mov_b32_e32 v99, v11
	v_mov_b32_e32 v86, v18
	v_mov_b32_e32 v87, v10
	v_pk_mul_f32 v[98:99], v[98:99], v[98:99]
	s_nop 0
	v_pk_fma_f32 v[86:87], v[86:87], v[86:87], v[98:99]
	v_mov_b32_e32 v98, v20
	v_mov_b32_e32 v99, v12
	v_pk_fma_f32 v[86:87], v[98:99], v[98:99], v[86:87]
	v_mov_b32_e32 v98, v21
	v_mov_b32_e32 v99, v13
	v_pk_fma_f32 v[86:87], v[98:99], v[98:99], v[86:87]
	s_nop 0
	v_add_f32_e32 v0, v0, v86
	v_add_f32_e32 v0, v0, v87
	ds_bpermute_b32 v86, v88, v0
	s_waitcnt lgkmcnt(0)
	v_add_f32_e32 v0, v0, v86
	ds_bpermute_b32 v86, v89, v0
	s_waitcnt lgkmcnt(0)
	v_add_f32_e32 v0, v0, v86
	ds_bpermute_b32 v86, v90, v0
	s_waitcnt lgkmcnt(0)
	v_add_f32_e32 v0, v0, v86
	ds_bpermute_b32 v86, v91, v0
	s_waitcnt lgkmcnt(0)
	v_add_f32_e32 v0, v0, v86
	ds_bpermute_b32 v86, v92, v0
	s_waitcnt lgkmcnt(0)
	v_add_f32_e32 v0, v0, v86
	ds_bpermute_b32 v86, v93, v0
	s_waitcnt lgkmcnt(0)
; DEVI void st_bf4(bf16_t* p, f32x4 v) { u32x2 u; u.x = cvt_pk_bf16(v[0], v[1]); u.y = cvt_pk_bf16(v[2], v[3]); *(u32x2*)p = u; }
; __device__ void phase_h(const float* __restrict__ x, const float* __restrict__ g, const float* __restrict__ sh, const float* __restrict__ sc, bf16_t* __restrict__ H) {
;     ...
;     const float rstd = rsqrtf(ss * (1.f / D) + 1e-6f);
; #pragma unroll
;     for (int i = 0; i < 8; ++i) {
;       const int c = i * 256 + lane * 4;
;       f32x4 gg = *(const f32x4*)(g + c), s1 = *(const f32x4*)(sc + c), s0 = *(const f32x4*)(sh + c);
;       f32x4 o = v[i] * rstd * gg * (1.f + s1) + s0;
;       st_bf4(H + (size_t)row * D + c, o);
;     }
	v_add_f32_e32 v0, v0, v86
	v_fmamk_f32 v0, v0, 0x3a000000, v180
	v_cmp_gt_f32_e32 vcc, s5, v0
	v_mul_f32_e32 v86, 0x4b800000, v0
	s_nop 0
	v_cndmask_b32_e32 v0, v0, v86, vcc
	v_rsq_f32_e32 v0, v0
	s_nop 0
	v_mul_f32_e32 v86, 0x45800000, v0
	v_cndmask_b32_e32 v0, v0, v86, vcc
	v_pk_mul_f32 v[86:87], v[96:97], v[0:1] op_sel_hi:[1,0]
	v_pk_mul_f32 v[94:95], v[94:95], v[0:1] op_sel_hi:[1,0]
	v_pk_mul_f32 v[86:87], v[8:9], v[86:87]
	v_pk_mul_f32 v[94:95], v[6:7], v[94:95]
	v_pk_fma_f32 v[96:97], v[78:79], v[86:87], v[4:5]
	v_lshlrev_b64 v[86:87], 12, v[38:39]
	v_pk_fma_f32 v[94:95], v[80:81], v[94:95], v[2:3]
	v_lshl_add_u64 v[86:87], v[84:85], 0, v[86:87]
	v_cvt_pk_bf16_f32 v94, v94, v95
	v_cvt_pk_bf16_f32 v95, v96, v97
	global_store_dwordx2 v[86:87], v[94:95], off
	s_nop 0
	v_pk_mul_f32 v[36:37], v[36:37], v[0:1] op_sel_hi:[1,0]
	v_pk_mul_f32 v[34:35], v[34:35], v[0:1] op_sel_hi:[1,0]
	v_pk_mul_f32 v[32:33], v[32:33], v[0:1] op_sel_hi:[1,0]
	v_pk_mul_f32 v[30:31], v[30:31], v[0:1] op_sel_hi:[1,0]
	v_pk_mul_f32 v[28:29], v[28:29], v[0:1] op_sel_hi:[1,0]
	v_pk_mul_f32 v[26:27], v[26:27], v[0:1] op_sel_hi:[1,0]
	v_pk_mul_f32 v[24:25], v[24:25], v[0:1] op_sel_hi:[1,0]
	v_pk_mul_f32 v[22:23], v[22:23], v[0:1] op_sel_hi:[1,0]
	v_pk_mul_f32 v[16:17], v[16:17], v[0:1] op_sel_hi:[1,0]
	v_pk_mul_f32 v[14:15], v[14:15], v[0:1] op_sel_hi:[1,0]
	v_pk_mul_f32 v[20:21], v[20:21], v[0:1] op_sel_hi:[1,0]
	v_pk_mul_f32 v[18:19], v[18:19], v[0:1] op_sel_hi:[1,0]
	v_pk_mul_f32 v[10:11], v[10:11], v[0:1] op_sel_hi:[1,0]
	v_add_u32_e32 v38, s4, v38
	v_pk_mul_f32 v[12:13], v[12:13], v[0:1] op_sel_hi:[1,0]
	v_cmp_lt_i32_e32 vcc, s87, v38
	s_or_b64 s[12:13], vcc, s[12:13]
	v_pk_mul_f32 v[34:35], v[112:113], v[34:35]
	v_pk_mul_f32 v[36:37], v[114:115], v[36:37]
	v_pk_add_f32 v[96:97], v[116:117], 1.0 op_sel_hi:[1,0]
	v_pk_add_f32 v[94:95], v[118:119], 1.0 op_sel_hi:[1,0]
	v_pk_fma_f32 v[34:35], v[96:97], v[34:35], v[120:121]
	v_pk_fma_f32 v[36:37], v[94:95], v[36:37], v[122:123]
	v_cvt_pk_bf16_f32 v34, v34, v35
	s_nop 0
	v_cvt_pk_bf16_f32 v35, v36, v37
	global_store_dwordx2 v[86:87], v[34:35], off offset:512
	s_nop 0
	v_pk_mul_f32 v[30:31], v[124:125], v[30:31]
	v_pk_mul_f32 v[32:33], v[126:127], v[32:33]
	v_pk_add_f32 v[36:37], v[128:129], 1.0 op_sel_hi:[1,0]
	v_pk_add_f32 v[34:35], v[130:131], 1.0 op_sel_hi:[1,0]
	v_pk_fma_f32 v[30:31], v[36:37], v[30:31], v[132:133]
	v_pk_fma_f32 v[32:33], v[34:35], v[32:33], v[134:135]
	v_cvt_pk_bf16_f32 v30, v30, v31
	s_nop 0
	v_cvt_pk_bf16_f32 v31, v32, v33
	global_store_dwordx2 v[86:87], v[30:31], off offset:1024
	s_nop 0
	v_pk_mul_f32 v[26:27], v[136:137], v[26:27]
	v_pk_mul_f32 v[28:29], v[138:139], v[28:29]
	v_pk_add_f32 v[32:33], v[140:141], 1.0 op_sel_hi:[1,0]
	v_pk_add_f32 v[30:31], v[142:143], 1.0 op_sel_hi:[1,0]
	v_pk_fma_f32 v[26:27], v[26:27], v[32:33], v[144:145]
	v_pk_fma_f32 v[28:29], v[28:29], v[30:31], v[146:147]
	v_cvt_pk_bf16_f32 v26, v26, v27
	s_nop 0
	v_cvt_pk_bf16_f32 v27, v28, v29
	global_store_dwordx2 v[86:87], v[26:27], off offset:1536
	s_nop 0
	v_pk_mul_f32 v[22:23], v[22:23], v[148:149]
	v_pk_mul_f32 v[24:25], v[24:25], v[150:151]
	v_pk_add_f32 v[28:29], v[152:153], 1.0 op_sel_hi:[1,0]
	v_pk_add_f32 v[26:27], v[154:155], 1.0 op_sel_hi:[1,0]
	v_pk_fma_f32 v[22:23], v[22:23], v[28:29], v[156:157]
	v_pk_fma_f32 v[24:25], v[24:25], v[26:27], v[158:159]
	v_cvt_pk_bf16_f32 v22, v22, v23
	s_nop 0
	v_cvt_pk_bf16_f32 v23, v24, v25
	global_store_dwordx2 v[86:87], v[22:23], off offset:2048
	s_nop 0
	v_pk_mul_f32 v[14:15], v[14:15], v[160:161]
	v_pk_mul_f32 v[16:17], v[16:17], v[162:163]
	v_pk_add_f32 v[24:25], v[164:165], 1.0 op_sel_hi:[1,0]
	v_pk_add_f32 v[22:23], v[166:167], 1.0 op_sel_hi:[1,0]
	v_pk_fma_f32 v[14:15], v[14:15], v[24:25], v[194:195]
	v_pk_fma_f32 v[16:17], v[16:17], v[22:23], v[196:197]
	v_cvt_pk_bf16_f32 v14, v14, v15
	s_nop 0
	v_cvt_pk_bf16_f32 v15, v16, v17
	global_store_dwordx2 v[86:87], v[14:15], off offset:2560
	s_nop 0
	v_pk_mul_f32 v[14:15], v[18:19], v[198:199]
	v_pk_mul_f32 v[16:17], v[20:21], v[200:201]
	v_pk_add_f32 v[20:21], v[202:203], 1.0 op_sel_hi:[1,0]
	v_pk_add_f32 v[18:19], v[204:205], 1.0 op_sel_hi:[1,0]
	v_pk_fma_f32 v[14:15], v[14:15], v[20:21], v[206:207]
	v_pk_fma_f32 v[16:17], v[16:17], v[18:19], v[208:209]
	v_cvt_pk_bf16_f32 v14, v14, v15
	s_nop 0
	v_cvt_pk_bf16_f32 v15, v16, v17
	global_store_dwordx2 v[86:87], v[14:15], off offset:3072
	s_nop 0
	v_pk_mul_f32 v[10:11], v[10:11], v[210:211]
	v_pk_add_f32 v[18:19], v[214:215], 1.0 op_sel_hi:[1,0]
	v_pk_mul_f32 v[12:13], v[12:13], v[212:213]
	v_pk_add_f32 v[20:21], v[216:217], 1.0 op_sel_hi:[1,0]
	v_pk_fma_f32 v[10:11], v[10:11], v[18:19], v[218:219]
	v_pk_fma_f32 v[12:13], v[12:13], v[20:21], v[220:221]
	v_cvt_pk_bf16_f32 v10, v10, v11
	s_nop 0
	v_cvt_pk_bf16_f32 v11, v12, v13
	global_store_dwordx2 v[86:87], v[10:11], off offset:3584
	s_andn2_b64 exec, exec, s[12:13]
	s_cbranch_execnz .LBB0_36

; DEVI int lbid() { int t = __builtin_amdgcn_workgroup_id_x(); asm volatile("" : "+s"(t)); return t; }
; DEVI int ltid() { int t = __builtin_amdgcn_workitem_id_x(); asm volatile("" : "+v"(t)); return t; }
; __device__ void phase_h(const float* __restrict__ x, const float* __restrict__ g, const float* __restrict__ sh, const float* __restrict__ sc, bf16_t* __restrict__ H) {
;   const int wave = ltid() >> 6, lane = ltid() & 63;
;   for (int row = lbid() * 8 + wave; row < T; row += gridDim.x * 8) {
;     const float* xr = x + (size_t)row * D;
;     f32x4 v[8]; float ss = 0.f;
; #pragma unroll
;     for (int i = 0; i < 8; ++i) { v[i] = __builtin_nontemporal_load((const f32x4*)(xr + i * 256 + lane * 4));   ss += v[i][0] * v[i][0] + v[i][1] * v[i][1] + v[i][2] * v[i][2] + v[i][3] * v[i][3]; }
.LBB0_195:
	v_mov_b32_e32 v0, v169
	v_readlane_b32 s0, v252, 0
	s_waitcnt vmcnt(0)
	v_ashrrev_i32_e32 v2, 6, v0
	v_mov_b32_e32 v0, v169
	s_nop 0
	v_lshl_add_u32 v38, s0, 3, v2
	v_cmp_gt_i32_e32 vcc, s74, v38
	s_and_saveexec_b64 s[10:11], vcc
	s_mov_b32 s4, 0x800000
	s_cbranch_execz .LBB0_198
	s_load_dwordx2 s[0:1], s[84:85], 0x28
	v_readlane_b32 s6, v251, 28
	v_lshlrev_b32_e32 v0, 2, v0
	v_readlane_b32 s7, v251, 29
	s_add_u32 s8, s6, 0x2000
	v_and_b32_e32 v26, 0xfc, v0
	s_addc_u32 s9, s7, 0
	v_lshlrev_b32_e32 v0, 2, v26
	s_lshl_b64 s[2:3], s[54:55], 2
	global_load_dwordx4 v[10:13], v0, s[8:9]
	s_waitcnt lgkmcnt(0)
	s_add_u32 s16, s0, s2
	s_addc_u32 s17, s1, s3
	global_load_dwordx4 v[2:5], v0, s[6:7]
	global_load_dwordx4 v[6:9], v0, s[16:17]
	v_and_b32_e32 v14, 64, v185
	v_xor_b32_e32 v16, 32, v185
	v_add_u32_e32 v14, 64, v14
	v_xor_b32_e32 v18, 16, v185
	v_cmp_lt_i32_e32 vcc, v16, v14
	v_xor_b32_e32 v20, 8, v185
	v_xor_b32_e32 v22, 4, v185
	v_cndmask_b32_e32 v28, v185, v16, vcc
	v_cmp_lt_i32_e32 vcc, v18, v14
	v_xor_b32_e32 v24, 2, v185
	v_xor_b32_e32 v27, 1, v185
	v_cndmask_b32_e32 v29, v185, v18, vcc
	v_cmp_lt_i32_e32 vcc, v20, v14
	v_lshl_add_u64 v[40:41], s[12:13], 0, v[0:1]
	v_lshl_add_u64 v[42:43], s[6:7], 0, v[0:1]
	v_cndmask_b32_e32 v30, v185, v20, vcc
	v_cmp_lt_i32_e32 vcc, v22, v14
	v_or_b32_e32 v16, 0x800, v0
	v_or_b32_e32 v18, 0xc00, v0
	v_cndmask_b32_e32 v31, v185, v22, vcc
	v_cmp_lt_i32_e32 vcc, v24, v14
	v_or_b32_e32 v20, 0x1000, v0
	v_or_b32_e32 v22, 0x1400, v0
	v_cndmask_b32_e32 v32, v185, v24, vcc
	v_cmp_lt_i32_e32 vcc, v27, v14
	v_or_b32_e32 v14, 0x400, v0
	v_or_b32_e32 v24, 0x1800, v0
	v_lshl_add_u64 v[62:63], s[16:17], 0, v[0:1]
	v_or_b32_e32 v0, 0x1c00, v0
	v_readlane_b32 s0, v251, 32
	v_mov_b32_e32 v15, v1
	v_mov_b32_e32 v17, v1
	v_mov_b32_e32 v19, v1
	v_mov_b32_e32 v21, v1
	v_mov_b32_e32 v23, v1
	v_mov_b32_e32 v25, v1
	v_cndmask_b32_e32 v27, v185, v27, vcc
	v_lshl_add_u64 v[70:71], s[16:17], 0, v[0:1]
	v_lshl_add_u64 v[72:73], s[8:9], 0, v[0:1]
	v_lshl_add_u64 v[78:79], s[6:7], 0, v[0:1]
	v_lshlrev_b32_e32 v0, 1, v26
	v_readlane_b32 s1, v251, 33
	v_lshlrev_b32_e32 v82, 2, v28
	v_lshlrev_b32_e32 v83, 2, v29
	v_lshlrev_b32_e32 v84, 2, v30
	v_lshlrev_b32_e32 v85, 2, v31
	v_lshlrev_b32_e32 v86, 2, v32
	v_lshlrev_b32_e32 v87, 2, v27
	v_lshl_add_u64 v[44:45], s[8:9], 0, v[14:15]
	v_lshl_add_u64 v[46:47], s[8:9], 0, v[16:17]
	v_lshl_add_u64 v[48:49], s[8:9], 0, v[18:19]
	v_lshl_add_u64 v[50:51], s[8:9], 0, v[20:21]
	v_lshl_add_u64 v[52:53], s[6:7], 0, v[20:21]
	v_lshl_add_u64 v[54:55], s[8:9], 0, v[22:23]
	v_lshl_add_u64 v[56:57], s[6:7], 0, v[22:23]
	v_lshl_add_u64 v[58:59], s[8:9], 0, v[24:25]
	v_lshl_add_u64 v[60:61], s[6:7], 0, v[24:25]
	v_lshl_add_u64 v[64:65], s[16:17], 0, v[20:21]
	v_lshl_add_u64 v[66:67], s[16:17], 0, v[22:23]
	v_lshl_add_u64 v[68:69], s[16:17], 0, v[24:25]
	v_lshl_add_u64 v[80:81], s[0:1], 0, v[0:1]
	s_mov_b64 s[12:13], 0
	s_waitcnt vmcnt(2)
	v_pk_add_f32 v[74:75], v[12:13], 1.0 op_sel_hi:[1,0]
	v_pk_add_f32 v[76:77], v[10:11], 1.0 op_sel_hi:[1,0]
	global_load_dwordx4 v[112:115], v[62:63], off offset:1024
	global_load_dwordx4 v[116:119], v[62:63], off offset:2048
	global_load_dwordx4 v[120:123], v[44:45], off
	global_load_dwordx4 v[124:127], v[42:43], off offset:3072
	global_load_dwordx4 v[128:131], v[42:43], off offset:1024
	global_load_dwordx4 v[132:135], v[42:43], off offset:2048
	global_load_dwordx4 v[136:139], v[46:47], off
	global_load_dwordx4 v[140:143], v[48:49], off
	global_load_dwordx4 v[144:147], v[62:63], off offset:3072
	global_load_dwordx4 v[148:151], v[64:65], off
	global_load_dwordx4 v[152:155], v[50:51], off
	global_load_dwordx4 v[156:159], v[52:53], off
	global_load_dwordx4 v[160:163], v[66:67], off
	global_load_dwordx4 v[164:167], v[54:55], off
	global_load_dwordx4 v[194:197], v[56:57], off
	global_load_dwordx4 v[198:201], v[68:69], off
	global_load_dwordx4 v[202:205], v[58:59], off
	global_load_dwordx4 v[206:209], v[60:61], off
	global_load_dwordx4 v[210:213], v[72:73], off
	global_load_dwordx4 v[214:217], v[70:71], off
	global_load_dwordx4 v[218:221], v[78:79], off
	s_waitcnt vmcnt(0)
.LBB0_197:
	v_ashrrev_i32_e32 v39, 31, v38
	v_lshlrev_b64 v[10:11], 13, v[38:39]
	v_lshl_add_u64 v[30:31], v[40:41], 0, v[10:11]
	v_add_co_u32_e32 v10, vcc, s57, v30
	global_load_dwordx4 v[22:25], v[30:31], off nt
	s_nop 0
	v_addc_co_u32_e32 v11, vcc, 0, v31, vcc
	global_load_dwordx4 v[26:29], v[10:11], off nt
	global_load_dwordx4 v[18:21], v[10:11], off offset:1024 nt
	global_load_dwordx4 v[14:17], v[10:11], off offset:2048 nt
	s_nop 0
	global_load_dwordx4 v[10:13], v[10:11], off offset:3072 nt
	s_nop 0
	global_load_dwordx4 v[88:91], v[30:31], off offset:1024 nt
	s_waitcnt vmcnt(4)
	v_mov_b32_e32 v34, v27
	s_waitcnt vmcnt(3)
	v_mov_b32_e32 v35, v19
	v_mov_b32_e32 v32, v26
	v_mov_b32_e32 v33, v18
	v_pk_mul_f32 v[34:35], v[34:35], v[34:35]
	s_waitcnt vmcnt(2)
	v_mov_b32_e32 v36, v14
	v_pk_fma_f32 v[32:33], v[32:33], v[32:33], v[34:35]
	v_mov_b32_e32 v34, v15
	s_waitcnt vmcnt(1)
	v_mov_b32_e32 v35, v11
	v_mov_b32_e32 v37, v10
	v_pk_mul_f32 v[34:35], v[34:35], v[34:35]
	v_mul_f32_e32 v0, v23, v23
	v_pk_fma_f32 v[34:35], v[36:37], v[36:37], v[34:35]
	s_waitcnt vmcnt(0)
	v_mul_f32_e32 v36, v89, v89
	v_fmac_f32_e32 v0, v22, v22
	v_fmac_f32_e32 v36, v88, v88
	v_fmac_f32_e32 v0, v24, v24
	v_fmac_f32_e32 v36, v90, v90
	v_fmac_f32_e32 v0, v25, v25
	v_fmac_f32_e32 v36, v91, v91
	v_add_f32_e32 v0, v0, v36
	v_mov_b32_e32 v36, v28
	v_mov_b32_e32 v37, v20
	v_pk_fma_f32 v[32:33], v[36:37], v[36:37], v[32:33]
	v_mov_b32_e32 v36, v16
	v_mov_b32_e32 v37, v12
	v_pk_fma_f32 v[34:35], v[36:37], v[36:37], v[34:35]
	v_mov_b32_e32 v36, v29
	v_mov_b32_e32 v37, v21
	v_pk_fma_f32 v[92:93], v[36:37], v[36:37], v[32:33]
	v_mov_b32_e32 v32, v17
	v_mov_b32_e32 v33, v13
	v_pk_fma_f32 v[94:95], v[32:33], v[32:33], v[34:35]
	global_load_dwordx4 v[34:37], v[30:31], off offset:2048 nt
	s_nop 0
	global_load_dwordx4 v[30:33], v[30:31], off offset:3072 nt
	s_waitcnt vmcnt(1)
; DEVI int lbid() { int t = __builtin_amdgcn_workgroup_id_x(); asm volatile("" : "+s"(t)); return t; }
; DEVI void st_bf4(bf16_t* p, f32x4 v) { u32x2 u; u.x = cvt_pk_bf16(v[0], v[1]); u.y = cvt_pk_bf16(v[2], v[3]); *(u32x2*)p = u; }
; __device__ void phase_h(const float* __restrict__ x, const float* __restrict__ g, const float* __restrict__ sh, const float* __restrict__ sc, bf16_t* __restrict__ H) {
;     ...
;   for (int row = lbid() * 8 + wave; row < T; row += gridDim.x * 8) {
;     const float* xr = x + (size_t)row * D;
;     f32x4 v[8]; float ss = 0.f;
; #pragma unroll
;     for (int i = 0; i < 8; ++i) { v[i] = __builtin_nontemporal_load((const f32x4*)(xr + i * 256 + lane * 4));   ss += v[i][0] * v[i][0] + v[i][1] * v[i][1] + v[i][2] * v[i][2] + v[i][3] * v[i][3]; }
;     ss = wave_sum(ss);
;     const float rstd = rsqrtf(ss * (1.f / D) + 1e-6f);
; #pragma unroll
;     for (int i = 0; i < 8; ++i) {
;       const int c = i * 256 + lane * 4;
;       f32x4 gg = *(const f32x4*)(g + c), s1 = *(const f32x4*)(sc + c), s0 = *(const f32x4*)(sh + c);
;       f32x4 o = v[i] * rstd * gg * (1.f + s1) + s0;
;       st_bf4(H + (size_t)row * D + c, o);
;     }
	v_mul_f32_e32 v96, v35, v35
	v_fmac_f32_e32 v96, v34, v34
	v_fmac_f32_e32 v96, v36, v36
	v_fmac_f32_e32 v96, v37, v37
	v_add_f32_e32 v0, v0, v96
	s_waitcnt vmcnt(0)
	v_mul_f32_e32 v96, v31, v31
	v_fmac_f32_e32 v96, v30, v30
	v_fmac_f32_e32 v96, v32, v32
	v_fmac_f32_e32 v96, v33, v33
	v_add_f32_e32 v0, v0, v96
	v_add_f32_e32 v0, v0, v92
	v_add_f32_e32 v0, v0, v93
	v_add_f32_e32 v0, v0, v94
	v_add_f32_e32 v0, v0, v95
	ds_bpermute_b32 v92, v82, v0
	s_waitcnt lgkmcnt(0)
	v_add_f32_e32 v0, v0, v92
	ds_bpermute_b32 v92, v83, v0
	s_waitcnt lgkmcnt(0)
	v_add_f32_e32 v0, v0, v92
	ds_bpermute_b32 v92, v84, v0
	s_waitcnt lgkmcnt(0)
	v_add_f32_e32 v0, v0, v92
	ds_bpermute_b32 v92, v85, v0
	s_waitcnt lgkmcnt(0)
	v_add_f32_e32 v0, v0, v92
	ds_bpermute_b32 v92, v86, v0
	s_waitcnt lgkmcnt(0)
	v_add_f32_e32 v0, v0, v92
	ds_bpermute_b32 v92, v87, v0
	s_waitcnt lgkmcnt(0)
	v_add_f32_e32 v0, v0, v92
	v_fmamk_f32 v0, v0, 0x3a000000, v180
	v_mul_f32_e32 v92, 0x4b800000, v0
	v_cmp_gt_f32_e32 vcc, s4, v0
	s_nop 1
	v_cndmask_b32_e32 v0, v0, v92, vcc
	v_rsq_f32_e32 v0, v0
	s_nop 0
	v_mul_f32_e32 v92, 0x45800000, v0
	v_cndmask_b32_e32 v0, v0, v92, vcc
	v_pk_mul_f32 v[96:97], v[90:91], v[0:1] op_sel_hi:[1,0]
	v_pk_mul_f32 v[98:99], v[88:89], v[0:1] op_sel_hi:[1,0]
	v_pk_mul_f32 v[36:37], v[36:37], v[0:1] op_sel_hi:[1,0]
	v_pk_mul_f32 v[34:35], v[34:35], v[0:1] op_sel_hi:[1,0]
	v_pk_mul_f32 v[22:23], v[22:23], v[0:1] op_sel_hi:[1,0]
	v_pk_mul_f32 v[24:25], v[24:25], v[0:1] op_sel_hi:[1,0]
	v_pk_mul_f32 v[22:23], v[6:7], v[22:23]
	v_pk_mul_f32 v[24:25], v[8:9], v[24:25]
	v_pk_fma_f32 v[22:23], v[76:77], v[22:23], v[2:3]
	v_pk_fma_f32 v[24:25], v[74:75], v[24:25], v[4:5]
	v_pk_mul_f32 v[20:21], v[20:21], v[0:1] op_sel_hi:[1,0]
	v_pk_mul_f32 v[18:19], v[18:19], v[0:1] op_sel_hi:[1,0]
	v_pk_mul_f32 v[16:17], v[16:17], v[0:1] op_sel_hi:[1,0]
	v_pk_mul_f32 v[14:15], v[14:15], v[0:1] op_sel_hi:[1,0]
	v_pk_mul_f32 v[10:11], v[10:11], v[0:1] op_sel_hi:[1,0]
	v_pk_mul_f32 v[12:13], v[12:13], v[0:1] op_sel_hi:[1,0]
	v_pk_mul_f32 v[104:105], v[112:113], v[98:99]
	v_pk_mul_f32 v[106:107], v[114:115], v[96:97]
	v_pk_mul_f32 v[92:93], v[116:117], v[34:35]
	v_pk_mul_f32 v[94:95], v[118:119], v[36:37]
	v_pk_add_f32 v[108:109], v[122:123], 1.0 op_sel_hi:[1,0]
	v_pk_add_f32 v[110:111], v[120:121], 1.0 op_sel_hi:[1,0]
	v_pk_fma_f32 v[106:107], v[108:109], v[106:107], v[130:131]
	v_pk_fma_f32 v[104:105], v[110:111], v[104:105], v[128:129]
	v_pk_add_f32 v[36:37], v[138:139], 1.0 op_sel_hi:[1,0]
	v_pk_add_f32 v[34:35], v[136:137], 1.0 op_sel_hi:[1,0]
	v_pk_fma_f32 v[94:95], v[36:37], v[94:95], v[134:135]
	v_pk_fma_f32 v[92:93], v[34:35], v[92:93], v[132:133]
	v_pk_mul_f32 v[34:35], v[32:33], v[0:1] op_sel_hi:[1,0]
	v_pk_mul_f32 v[36:37], v[30:31], v[0:1] op_sel_hi:[1,0]
	v_pk_mul_f32 v[36:37], v[144:145], v[36:37]
	v_pk_mul_f32 v[30:31], v[146:147], v[34:35]
	v_pk_add_f32 v[32:33], v[142:143], 1.0 op_sel_hi:[1,0]
	v_pk_add_f32 v[34:35], v[140:141], 1.0 op_sel_hi:[1,0]
	v_pk_fma_f32 v[30:31], v[30:31], v[32:33], v[126:127]
	v_pk_fma_f32 v[32:33], v[36:37], v[34:35], v[124:125]
	v_pk_mul_f32 v[34:35], v[28:29], v[0:1] op_sel_hi:[1,0]
	v_pk_mul_f32 v[36:37], v[26:27], v[0:1] op_sel_hi:[1,0]
	v_pk_mul_f32 v[88:89], v[36:37], v[148:149]
	v_pk_mul_f32 v[90:91], v[34:35], v[150:151]
	v_pk_add_f32 v[26:27], v[152:153], 1.0 op_sel_hi:[1,0]
	v_pk_add_f32 v[28:29], v[154:155], 1.0 op_sel_hi:[1,0]
	v_pk_fma_f32 v[88:89], v[88:89], v[26:27], v[156:157]
	v_cvt_pk_bf16_f32 v26, v22, v23
	v_lshlrev_b64 v[22:23], 12, v[38:39]
	v_pk_fma_f32 v[90:91], v[90:91], v[28:29], v[158:159]
	v_cvt_pk_bf16_f32 v27, v24, v25
	v_cvt_pk_bf16_f32 v28, v104, v105
	v_cvt_pk_bf16_f32 v29, v106, v107
	v_lshl_add_u64 v[22:23], v[80:81], 0, v[22:23]
	v_cvt_pk_bf16_f32 v34, v92, v93
	v_cvt_pk_bf16_f32 v35, v94, v95
	global_store_dwordx2 v[22:23], v[26:27], off
	s_nop 0
	global_store_dwordx2 v[22:23], v[28:29], off offset:512
	global_store_dwordx2 v[22:23], v[34:35], off offset:1024
	v_cvt_pk_bf16_f32 v28, v32, v33
	v_cvt_pk_bf16_f32 v29, v30, v31
	global_store_dwordx2 v[22:23], v[28:29], off offset:1536
	v_cvt_pk_bf16_f32 v32, v88, v89
	v_cvt_pk_bf16_f32 v33, v90, v91
	global_store_dwordx2 v[22:23], v[32:33], off offset:2048
	v_add_u32_e32 v38, s28, v38
	v_cmp_lt_i32_e32 vcc, s87, v38
	s_or_b64 s[12:13], vcc, s[12:13]
	v_pk_mul_f32 v[18:19], v[18:19], v[160:161]
	v_pk_mul_f32 v[20:21], v[20:21], v[162:163]
	v_pk_add_f32 v[88:89], v[164:165], 1.0 op_sel_hi:[1,0]
	v_pk_add_f32 v[36:37], v[166:167], 1.0 op_sel_hi:[1,0]
	v_pk_fma_f32 v[18:19], v[18:19], v[88:89], v[194:195]
	v_pk_fma_f32 v[30:31], v[20:21], v[36:37], v[196:197]
	v_cvt_pk_bf16_f32 v28, v18, v19
	v_cvt_pk_bf16_f32 v29, v30, v31
	global_store_dwordx2 v[22:23], v[28:29], off offset:2560
	v_pk_mul_f32 v[14:15], v[14:15], v[198:199]
	v_pk_mul_f32 v[16:17], v[16:17], v[200:201]
	v_pk_add_f32 v[36:37], v[204:205], 1.0 op_sel_hi:[1,0]
	v_pk_add_f32 v[88:89], v[202:203], 1.0 op_sel_hi:[1,0]
	v_pk_fma_f32 v[16:17], v[16:17], v[36:37], v[208:209]
	v_pk_fma_f32 v[14:15], v[14:15], v[88:89], v[206:207]
	v_pk_mul_f32 v[10:11], v[10:11], v[214:215]
	v_cvt_pk_bf16_f32 v14, v14, v15
	v_cvt_pk_bf16_f32 v15, v16, v17
	v_pk_add_f32 v[16:17], v[210:211], 1.0 op_sel_hi:[1,0]
	global_store_dwordx2 v[22:23], v[14:15], off offset:3072
	v_pk_mul_f32 v[12:13], v[12:13], v[216:217]
	v_pk_add_f32 v[14:15], v[212:213], 1.0 op_sel_hi:[1,0]
	v_pk_fma_f32 v[10:11], v[10:11], v[16:17], v[218:219]
	v_pk_fma_f32 v[12:13], v[12:13], v[14:15], v[220:221]
	v_cvt_pk_bf16_f32 v10, v10, v11
	s_nop 0
	v_cvt_pk_bf16_f32 v11, v12, v13
	global_store_dwordx2 v[22:23], v[10:11], off offset:3584
	s_andn2_b64 exec, exec, s[12:13]
	s_cbranch_execnz .LBB0_197
